# attention tile loop: next tile's K/V staging LDS writes issued inside the second sub-tile's map-1 PV MFMAs instead of after them
# baseline (speedup 1.0000x reference)
; #define LAS __attribute__((address_space(3)))
; __device__ __forceinline__ void dattn_unit(LAS unsigned char* lds, int b, int h, int qb, const bf16* Q, const bf16* K, const bf16* V, bf16* YB, float lam, const float* subg, float oml, int tid) {
;     ...
;     for (int t = 0; t < NT; ++t) {
;         if (t + 1 < NT) { const size_t adv = (size_t)(t + 1) * 64 * 1024; kr0 = *(const v4u*)(kg + adv); kr1 = *(const v4u*)(kg + adv + 64); vr0 = *(const v4u*)(vg + adv); vr1 = *(const v4u*)(vg + adv + 8); }
;         const LAS bf16* Ks = (const LAS bf16*)(lds + (t & 1) * AT_BUF + AT_KS); const LAS bf16* Vt = (const LAS bf16*)(lds + (t & 1) * AT_BUF + AT_VT);
;         const int kvbase = t * 64;
.Lstage_nw:
	s_add_i32 s59, s59, 1
	s_bitcmp1_b32 s59, 0
	s_cselect_b32 s18, 0x9000, 0
	s_add_i32 s60, s18, 0
	s_addk_i32 s57, 0x100
	s_add_i32 s58, s58, 64
	s_add_u32 s98, s98, s14
	s_addc_u32 s99, s99, s15
	s_add_u32 s100, s100, s14
	s_addc_u32 s101, s101, s15
	s_cmp_lg_u32 s56, s57
	s_branch .Lstage_join

; __device__ __forceinline__ void dattn_unit(LAS unsigned char* lds, int b, int h, int qb, const bf16* Q, const bf16* K, const bf16* V, bf16* YB, float lam, const float* subg, float oml, int tid) {
;     ...
;         if (t + 1 < NT) AT_STAGE((t + 1) & 1);
;         __syncthreads();
;     }
.Lstage_join:
	s_waitcnt lgkmcnt(0)
	s_barrier
	s_cbranch_scc0 .LBB0_249

; #define LAS __attribute__((address_space(3)))
; #define AT_RAISE(MP) do { if (trig[MP]) { const float dl = fmaxf(__builtin_amdgcn_logf(pmx[MP]), 0.f), al = __builtin_amdgcn_exp2f(-dl); mref[MP] += dl; lsum[MP] *= al; \
;                 _Pragma("unroll") for (int cb = 0; cb < 4; ++cb) o[MP][cb] = o[MP][cb] * al; } } while (0)
; __device__ __forceinline__ void dattn_unit(LAS unsigned char* lds, int b, int h, int qb, const bf16* Q, const bf16* K, const bf16* V, bf16* YB, float lam, const float* subg, float oml, int tid) {
;     ...
;             for (int cb = 0; cb < 4; ++cb) { const LAS bf16* vp = Vt + (32 * cb + ql) * 72 + 32 * sub + 4 * hi;
;                 const v2u a0 = *(const LAS v2u*)(vp), a1 = *(const LAS v2u*)(vp + 8), a2 = *(const LAS v2u*)(vp + 16), a3 = *(const LAS v2u*)(vp + 24);
;                 const v4u f0 = {a0.x, a0.y, a1.x, a1.y}, f1 = {a2.x, a2.y, a3.x, a3.y};
;                 o[0][cb] = __builtin_amdgcn_mfma_f32_32x32x16_bf16(__builtin_bit_cast(bf16x8, f0), pA0, o[0][cb], 0, 0, 0);
;                 o[1][cb] = __builtin_amdgcn_mfma_f32_32x32x16_bf16(__builtin_bit_cast(bf16x8, f0), pA1, o[1][cb], 0, 0, 0);
;                 o[0][cb] = __builtin_amdgcn_mfma_f32_32x32x16_bf16(__builtin_bit_cast(bf16x8, f1), pB0, o[0][cb], 0, 0, 0);
;                 o[1][cb] = __builtin_amdgcn_mfma_f32_32x32x16_bf16(__builtin_bit_cast(bf16x8, f1), pB1, o[1][cb], 0, 0, 0); }
;             AT_RAISE(0); AT_RAISE(1);
.LBB0_245:
	v_cvt_pk_bf16_f32 v152, v155, v129
	v_cvt_pk_bf16_f32 v153, v130, v131
	v_cvt_pk_bf16_f32 v154, v132, v156
	v_cvt_pk_bf16_f32 v155, v157, v158
	v_cvt_pk_bf16_f32 v130, v133, v134
	v_cvt_pk_bf16_f32 v131, v135, v136
	v_cvt_pk_bf16_f32 v132, v137, v138
	v_cvt_pk_bf16_f32 v133, v139, v140
	s_xor_b32 s18, s38, 0x9000
	v_add3_u32 v148, s18, v196, v180
	v_add3_u32 v149, s18, v197, v195
	s_andn2_b64 vcc, exec, s[48:49]
	s_nop 0
	v_mfma_f32_32x32x16_bf16 v[64:79], v[222:225], v[152:155], v[64:79]
	s_waitcnt vmcnt(3)
	ds_write_b128 v148, v[168:171]
	v_mfma_f32_32x32x16_bf16 v[64:79], v[226:229], v[130:133], v[64:79]
	s_waitcnt vmcnt(2)
	ds_write_b128 v148, v[172:175] offset:9216
	v_mfma_f32_32x32x16_bf16 v[32:47], v[230:233], v[152:155], v[32:47]
	s_waitcnt vmcnt(1)
	ds_write_b16 v149, v164 offset:18432
	ds_write_b16_d16_hi v149, v164 offset:18576
	ds_write_b16 v149, v165 offset:18720
	v_mfma_f32_32x32x16_bf16 v[32:47], v[234:237], v[130:133], v[32:47]
	ds_write_b16_d16_hi v149, v165 offset:18864
	ds_write_b16 v149, v166 offset:19008
	ds_write_b16_d16_hi v149, v166 offset:19152
	v_mfma_f32_32x32x16_bf16 v[96:111], v[212:215], v[152:155], v[96:111]
	ds_write_b16 v149, v167 offset:19296
	ds_write_b16_d16_hi v149, v167 offset:19440
	s_waitcnt vmcnt(0)
	ds_write_b16 v149, v160 offset:19584
	v_mfma_f32_32x32x16_bf16 v[96:111], v[200:203], v[130:133], v[96:111]
	ds_write_b16_d16_hi v149, v160 offset:19728
	ds_write_b16 v149, v161 offset:19872
	ds_write_b16_d16_hi v149, v161 offset:20016
	v_mfma_f32_32x32x16_bf16 v[0:15], v[238:241], v[152:155], v[0:15]
	ds_write_b16 v149, v162 offset:20160
	ds_write_b16_d16_hi v149, v162 offset:20304
	v_mfma_f32_32x32x16_bf16 v[0:15], v[218:221], v[130:133], v[0:15]
	ds_write_b16 v149, v163 offset:20448
	ds_write_b16_d16_hi v149, v163 offset:20592
	s_cbranch_vccnz .LBB0_247
	v_log_f32_e32 v129, v146
	s_nop 0
	v_max_f32_e32 v129, 0, v129
	v_exp_f32_e64 v130, -v129
	v_add_f32_e32 v190, v190, v129
	s_nop 1
	v_pk_mul_f32 v[126:127], v[130:131], v[126:127] op_sel_hi:[0,1]
	v_pk_mul_f32 v[124:125], v[130:131], v[124:125] op_sel_hi:[0,1]
	v_pk_mul_f32 v[122:123], v[130:131], v[122:123] op_sel_hi:[0,1]
	v_pk_mul_f32 v[120:121], v[130:131], v[120:121] op_sel_hi:[0,1]
	v_pk_mul_f32 v[118:119], v[130:131], v[118:119] op_sel_hi:[0,1]
	v_pk_mul_f32 v[116:117], v[130:131], v[116:117] op_sel_hi:[0,1]
	v_pk_mul_f32 v[114:115], v[130:131], v[114:115] op_sel_hi:[0,1]
	v_pk_mul_f32 v[112:113], v[130:131], v[112:113] op_sel_hi:[0,1]
	v_pk_mul_f32 v[94:95], v[130:131], v[94:95] op_sel_hi:[0,1]
	v_pk_mul_f32 v[92:93], v[130:131], v[92:93] op_sel_hi:[0,1]
	v_pk_mul_f32 v[90:91], v[130:131], v[90:91] op_sel_hi:[0,1]
	v_pk_mul_f32 v[88:89], v[130:131], v[88:89] op_sel_hi:[0,1]
	v_pk_mul_f32 v[86:87], v[130:131], v[86:87] op_sel_hi:[0,1]
	v_pk_mul_f32 v[84:85], v[130:131], v[84:85] op_sel_hi:[0,1]
	v_pk_mul_f32 v[82:83], v[130:131], v[82:83] op_sel_hi:[0,1]
	v_pk_mul_f32 v[80:81], v[130:131], v[80:81] op_sel_hi:[0,1]
	v_pk_mul_f32 v[62:63], v[130:131], v[62:63] op_sel_hi:[0,1]
	v_pk_mul_f32 v[60:61], v[130:131], v[60:61] op_sel_hi:[0,1]
	v_pk_mul_f32 v[58:59], v[130:131], v[58:59] op_sel_hi:[0,1]
	v_pk_mul_f32 v[56:57], v[130:131], v[56:57] op_sel_hi:[0,1]
	v_pk_mul_f32 v[54:55], v[130:131], v[54:55] op_sel_hi:[0,1]
	v_pk_mul_f32 v[52:53], v[130:131], v[52:53] op_sel_hi:[0,1]
	v_pk_mul_f32 v[50:51], v[130:131], v[50:51] op_sel_hi:[0,1]
	v_pk_mul_f32 v[48:49], v[130:131], v[48:49] op_sel_hi:[0,1]
	v_pk_mul_f32 v[30:31], v[130:131], v[30:31] op_sel_hi:[0,1]
	v_pk_mul_f32 v[28:29], v[130:131], v[28:29] op_sel_hi:[0,1]
	v_pk_mul_f32 v[26:27], v[130:131], v[26:27] op_sel_hi:[0,1]
	v_pk_mul_f32 v[24:25], v[130:131], v[24:25] op_sel_hi:[0,1]
	v_pk_mul_f32 v[22:23], v[130:131], v[22:23] op_sel_hi:[0,1]
	v_pk_mul_f32 v[20:21], v[130:131], v[20:21] op_sel_hi:[0,1]
	v_pk_mul_f32 v[18:19], v[130:131], v[18:19] op_sel_hi:[0,1]
	v_pk_mul_f32 v[16:17], v[130:131], v[16:17] op_sel_hi:[0,1]
	v_mul_f32_e32 v179, v179, v130
